# out-proj epilogue: row-scale loads hoisted, 4 residual loads per row issued together, row-sumsq atomics deferred to epilogue end
# baseline (speedup 1.0000x reference)
; DI void ss_add(ssacc_t* p, float v) { atomicAdd(p, (ssacc_t)__float2ull_rn(v * 4294967296.f)); }
; DI float ss_get(const ssacc_t* p) { const ssacc_t v = *p; return (float)(unsigned)(v >> 32) + (float)(unsigned)(v & 0xffffffffull) * 2.3283064365386963e-10f; }
; DI float quad_sum(float s) { s += __shfl_xor(s, 16); s += __shfl_xor(s, 32); return s; }
; DI float sq8(const f32x4& a, const f32x4& b) { return (a[0] * a[0] + a[1] * a[1]) + (a[2] * a[2] + a[3] * a[3]) + (b[0] * b[0] + b[1] * b[1]) + (b[2] * b[2] + b[3] * b[3]); }
; DI u32x4 pack8(const f32x4& a, const f32x4& b) { u32x4 w; w.x = cvtpk(a[0], a[1]); w.y = cvtpk(a[2], a[3]); w.z = cvtpk(b[0], b[1]); w.w = cvtpk(b[2], b[3]); return w; }
;     DI void operator()(const Acc& acc, const Unit& u, int wr, int wc, int fr, int fq) const {
;         const ssacc_t* ss_dil = (const ssacc_t*)(ws + WS_SS) + (size_t)(SS_DIL + l) * M_; ssacc_t* ssx1 = (ssacc_t*)(ws + WS_SS) + (size_t)(SS_X1 + l) * M_;
;         float* X = (float*)(ws + WS_X); bf16_t* XB = (bf16_t*)(ws + WS_XB);
; #pragma unroll
;         for (int ai = 0; ai < 2; ++ai)
; #pragma unroll
;             for (int m = 0; m < 4; ++m) {
;                 asm volatile("" ::: "memory");
;                 const int row = u.pm * 256 + ai * 128 + wr * 64 + m * 16 + fr;
;                 const float rs = rsqrtf(ss_get(ss_dil + row) * (1.f / 512.f) + EPS_);
;                 float sq = 0.f;
; #pragma unroll
;                 for (int bj = 0; bj < 2; ++bj) {
;                     const size_t off = (size_t)row * 2048 + u.pn * 256 + bj * 128 + wc * 32 + 8 * fq;
;                     const f32x4 v0 = *(const f32x4*)(xin + off) + acc[ai][bj][m][0] * rs, v1 = *(const f32x4*)(xin + off + 4) + acc[ai][bj][m][1] * rs;
;                     *(f32x4*)(X + off) = v0; *(f32x4*)(X + off + 4) = v1; *(u32x4*)(XB + off) = pack8(v0, v1); sq += sq8(v0, v1);
;                 }
;                 sq = quad_sum(sq); if (fq == 0) ss_add(ssx1 + row, sq);
;             }
;     }
.LBB0_1278:
	v_lshl_add_u32 v146, s41, 8, v141
	v_ashrrev_i32_e32 v147, 31, v146
	v_lshl_add_u64 v[148:149], v[146:147], 3, s[56:57]
	global_load_dwordx2 v[208:209], v[148:149], off
	global_load_dwordx2 v[210:211], v[148:149], off offset:128
	global_load_dwordx2 v[212:213], v[148:149], off offset:256
	global_load_dwordx2 v[214:215], v[148:149], off offset:384
	global_load_dwordx2 v[216:217], v[148:149], off offset:1024
	global_load_dwordx2 v[218:219], v[148:149], off offset:1152
	global_load_dwordx2 v[220:221], v[148:149], off offset:1280
	global_load_dwordx2 v[222:223], v[148:149], off offset:1408
	s_min_u32 s16, s88, 32
	s_sub_i32 s17, 32, s16
	s_lshl_b32 s4, s40, 8
	s_ashr_i32 s14, s4, 31
	v_mov_b32_e32 v131, s14
	v_or_b32_e32 v130, s4, v140
	s_waitcnt vmcnt(7)
	v_mov_b32_e32 v148, v208
	v_mov_b32_e32 v149, v209
	v_mov_b32_e32 v128, v149
	v_lshlrev_b64 v[150:151], s16, v[128:129]
	v_min_u32_e32 v128, 1, v150
	v_or_b32_e32 v128, v151, v128
	v_cvt_f32_u32_e32 v128, v128
	v_cvt_f32_u32_e32 v148, v148
	v_ldexp_f32 v128, v128, s17
	v_fmac_f32_e32 v128, 0x2f800000, v148
	v_fmamk_f32 v128, v128, 0x3b000000, v195
	v_cmp_gt_f32_e32 vcc, s27, v128
	v_mul_f32_e32 v148, 0x4b800000, v128
	s_nop 0
	v_cndmask_b32_e32 v128, v128, v148, vcc
	v_rsq_f32_e32 v128, v128
	s_nop 0
	v_mul_f32_e32 v148, 0x45800000, v128
	v_cndmask_b32_e32 v128, v128, v148, vcc
	v_lshlrev_b64 v[148:149], 11, v[146:147]
	v_lshl_add_u64 v[148:149], v[148:149], 0, v[130:131]
	v_lshlrev_b64 v[164:165], 2, v[148:149]
	s_waitcnt lgkmcnt(0)
	v_lshl_add_u64 v[150:151], s[8:9], 0, v[164:165]
	global_load_dwordx4 v[156:159], v[150:151], off offset:16
	global_load_dwordx4 v[160:163], v[150:151], off
	global_load_dwordx4 v[166:169], v[150:151], off offset:528
	global_load_dwordx4 v[170:173], v[150:151], off offset:512
	s_waitcnt vmcnt(3)
	v_pk_fma_f32 v[124:125], v[124:125], v[128:129], v[156:157] op_sel_hi:[1,0,1]
	s_waitcnt vmcnt(2)
	v_pk_fma_f32 v[122:123], v[122:123], v[128:129], v[162:163] op_sel_hi:[1,0,1]
	v_pk_fma_f32 v[120:121], v[120:121], v[128:129], v[160:161] op_sel_hi:[1,0,1]
	v_lshl_add_u64 v[156:157], s[60:61], 0, v[164:165]
	v_pk_fma_f32 v[126:127], v[126:127], v[128:129], v[158:159] op_sel_hi:[1,0,1]
	global_store_dwordx4 v[156:157], v[120:123], off
	global_store_dwordx4 v[156:157], v[124:127], off offset:16
	v_cvt_pk_bf16_f32 v156, v120, v121
	v_mul_f32_e32 v121, v121, v121
	v_fmac_f32_e32 v121, v120, v120
	v_mul_f32_e32 v120, v123, v123
	v_fmac_f32_e32 v120, v122, v122
	v_add_f32_e32 v120, v121, v120
	v_mul_f32_e32 v121, v125, v125
	v_fmac_f32_e32 v121, v124, v124
	v_cvt_pk_bf16_f32 v157, v122, v123
	v_cvt_pk_bf16_f32 v158, v124, v125
	v_cvt_pk_bf16_f32 v159, v126, v127
	v_lshl_add_u64 v[160:161], v[148:149], 1, s[62:63]
	v_add_f32_e32 v120, v121, v120
	v_mul_f32_e32 v121, v127, v127
	global_store_dwordx4 v[160:161], v[156:159], off
	v_fmac_f32_e32 v121, v126, v126
	v_add_f32_e32 v155, v121, v120
	v_or_b32_e32 v148, 0x80, v148
	s_waitcnt vmcnt(3)
	v_mov_b32_e32 v120, v166
	v_mov_b32_e32 v121, v167
	v_mov_b32_e32 v122, v168
	v_mov_b32_e32 v123, v169
	v_mov_b32_e32 v124, v170
	v_mov_b32_e32 v125, v171
	v_mov_b32_e32 v126, v172
	v_mov_b32_e32 v127, v173
	v_pk_fma_f32 v[116:117], v[116:117], v[128:129], v[120:121] op_sel_hi:[1,0,1]
	v_pk_fma_f32 v[114:115], v[114:115], v[128:129], v[126:127] op_sel_hi:[1,0,1]
	v_pk_fma_f32 v[112:113], v[112:113], v[128:129], v[124:125] op_sel_hi:[1,0,1]
	v_lshl_add_u64 v[120:121], v[148:149], 2, s[60:61]
	v_pk_fma_f32 v[118:119], v[118:119], v[128:129], v[122:123] op_sel_hi:[1,0,1]
	global_store_dwordx4 v[120:121], v[112:115], off
	global_store_dwordx4 v[120:121], v[116:119], off offset:16
	v_cvt_pk_bf16_f32 v120, v112, v113
	v_mul_f32_e32 v113, v113, v113
	v_fmac_f32_e32 v113, v112, v112
	v_mul_f32_e32 v112, v115, v115
	v_fmac_f32_e32 v112, v114, v114
	v_add_f32_e32 v112, v113, v112
	v_mul_f32_e32 v113, v117, v117
	v_fmac_f32_e32 v113, v116, v116
	v_add_f32_e32 v112, v113, v112
	v_mul_f32_e32 v113, v119, v119
	v_cvt_pk_bf16_f32 v121, v114, v115
	v_fmac_f32_e32 v113, v118, v118
	v_and_b32_e32 v114, 64, v199
	v_add_f32_e32 v112, v113, v112
	v_xor_b32_e32 v113, 16, v199
	v_add_u32_e32 v114, 64, v114
	v_cmp_lt_i32_e32 vcc, v113, v114
	v_add_f32_e32 v112, v155, v112
	v_cvt_pk_bf16_f32 v122, v116, v117
	v_cndmask_b32_e32 v113, v199, v113, vcc
	v_lshlrev_b32_e32 v115, 2, v113
	ds_bpermute_b32 v113, v115, v112
	v_cvt_pk_bf16_f32 v123, v118, v119
	v_lshl_add_u64 v[124:125], v[148:149], 1, s[62:63]
	global_store_dwordx4 v[124:125], v[120:123], off
	s_waitcnt lgkmcnt(0)
	v_add_f32_e32 v112, v112, v113
	v_xor_b32_e32 v113, 32, v199
	v_cmp_lt_i32_e32 vcc, v113, v114
	s_nop 1
	v_cndmask_b32_e32 v113, v199, v113, vcc
	v_lshlrev_b32_e32 v120, 2, v113
	ds_bpermute_b32 v113, v120, v112
	s_and_saveexec_b64 s[14:15], s[48:49]
	s_cbranch_execz .LBB0_1280
	s_waitcnt lgkmcnt(0)
	v_add_f32_e32 v112, v112, v113
	v_mul_f32_e32 v112, 0x4f800000, v112
	v_rndne_f32_e32 v112, v112
	v_mul_f32_e32 v113, 0x2f800000, v112
	v_floor_f32_e32 v113, v113
	v_fmac_f32_e32 v112, 0xcf800000, v113
	v_cvt_u32_f32_e32 v112, v112
	v_cvt_u32_f32_e32 v113, v113
	v_lshl_add_u64 v[224:225], v[146:147], 3, s[58:59]
	v_mov_b32_e32 v226, v112
	v_mov_b32_e32 v227, v113
; DI void ss_add(ssacc_t* p, float v) { atomicAdd(p, (ssacc_t)__float2ull_rn(v * 4294967296.f)); }
; DI float ss_get(const ssacc_t* p) { const ssacc_t v = *p; return (float)(unsigned)(v >> 32) + (float)(unsigned)(v & 0xffffffffull) * 2.3283064365386963e-10f; }
; DI float quad_sum(float s) { s += __shfl_xor(s, 16); s += __shfl_xor(s, 32); return s; }
; DI float sq8(const f32x4& a, const f32x4& b) { return (a[0] * a[0] + a[1] * a[1]) + (a[2] * a[2] + a[3] * a[3]) + (b[0] * b[0] + b[1] * b[1]) + (b[2] * b[2] + b[3] * b[3]); }
; DI u32x4 pack8(const f32x4& a, const f32x4& b) { u32x4 w; w.x = cvtpk(a[0], a[1]); w.y = cvtpk(a[2], a[3]); w.z = cvtpk(b[0], b[1]); w.w = cvtpk(b[2], b[3]); return w; }
;     DI void operator()(const Acc& acc, const Unit& u, int wr, int wc, int fr, int fq) const {
;         const ssacc_t* ss_dil = (const ssacc_t*)(ws + WS_SS) + (size_t)(SS_DIL + l) * M_; ssacc_t* ssx1 = (ssacc_t*)(ws + WS_SS) + (size_t)(SS_X1 + l) * M_;
;         float* X = (float*)(ws + WS_X); bf16_t* XB = (bf16_t*)(ws + WS_XB);
; #pragma unroll
;         for (int ai = 0; ai < 2; ++ai)
; #pragma unroll
;             for (int m = 0; m < 4; ++m) {
;                 asm volatile("" ::: "memory");
;                 const int row = u.pm * 256 + ai * 128 + wr * 64 + m * 16 + fr;
;                 const float rs = rsqrtf(ss_get(ss_dil + row) * (1.f / 512.f) + EPS_);
;                 float sq = 0.f;
; #pragma unroll
;                 for (int bj = 0; bj < 2; ++bj) {
;                     const size_t off = (size_t)row * 2048 + u.pn * 256 + bj * 128 + wc * 32 + 8 * fq;
;                     const f32x4 v0 = *(const f32x4*)(xin + off) + acc[ai][bj][m][0] * rs, v1 = *(const f32x4*)(xin + off + 4) + acc[ai][bj][m][1] * rs;
;                     *(f32x4*)(X + off) = v0; *(f32x4*)(X + off + 4) = v1; *(u32x4*)(XB + off) = pack8(v0, v1); sq += sq8(v0, v1);
;                 }
;                 sq = quad_sum(sq); if (fq == 0) ss_add(ssx1 + row, sq);
;             }
;     }
.LBB0_1280:
	s_or_b64 exec, exec, s[14:15]
	v_or_b32_e32 v112, 16, v146
	s_waitcnt lgkmcnt(0)
	v_ashrrev_i32_e32 v113, 31, v112
	s_waitcnt vmcnt(9)
	v_mov_b32_e32 v116, v210
	v_mov_b32_e32 v117, v211
	v_mov_b32_e32 v128, v117
	v_lshlrev_b64 v[118:119], s16, v[128:129]
	v_min_u32_e32 v114, 1, v118
	v_or_b32_e32 v114, v119, v114
	v_cvt_f32_u32_e32 v114, v114
	v_cvt_f32_u32_e32 v116, v116
	v_ldexp_f32 v114, v114, s17
	v_fmac_f32_e32 v114, 0x2f800000, v116
	v_fmamk_f32 v114, v114, 0x3b000000, v195
	v_cmp_gt_f32_e32 vcc, s27, v114
	v_mul_f32_e32 v116, 0x4b800000, v114
	s_nop 0
	v_cndmask_b32_e32 v114, v114, v116, vcc
	v_rsq_f32_e32 v114, v114
	s_nop 0
	v_mul_f32_e32 v116, 0x45800000, v114
	v_cndmask_b32_e32 v114, v114, v116, vcc
	v_lshlrev_b64 v[116:117], 11, v[112:113]
	v_lshl_add_u64 v[116:117], v[116:117], 0, v[130:131]
	v_lshlrev_b64 v[126:127], 2, v[116:117]
	v_lshl_add_u64 v[118:119], s[8:9], 0, v[126:127]
	global_load_dwordx4 v[122:125], v[118:119], off offset:16
	global_load_dwordx4 v[148:151], v[118:119], off
	global_load_dwordx4 v[166:169], v[118:119], off offset:528
	global_load_dwordx4 v[170:173], v[118:119], off offset:512
	s_waitcnt vmcnt(3)
	v_pk_fma_f32 v[108:109], v[108:109], v[114:115], v[122:123] op_sel_hi:[1,0,1]
	s_waitcnt vmcnt(2)
	v_pk_fma_f32 v[106:107], v[106:107], v[114:115], v[150:151] op_sel_hi:[1,0,1]
	v_pk_fma_f32 v[104:105], v[104:105], v[114:115], v[148:149] op_sel_hi:[1,0,1]
	v_lshl_add_u64 v[122:123], s[60:61], 0, v[126:127]
	v_pk_fma_f32 v[110:111], v[110:111], v[114:115], v[124:125] op_sel_hi:[1,0,1]
	global_store_dwordx4 v[122:123], v[104:107], off
	global_store_dwordx4 v[122:123], v[108:111], off offset:16
	v_cvt_pk_bf16_f32 v122, v104, v105
	v_mul_f32_e32 v105, v105, v105
	v_fmac_f32_e32 v105, v104, v104
	v_mul_f32_e32 v104, v107, v107
	v_fmac_f32_e32 v104, v106, v106
	v_add_f32_e32 v104, v105, v104
	v_mul_f32_e32 v105, v109, v109
	v_fmac_f32_e32 v105, v108, v108
	v_cvt_pk_bf16_f32 v123, v106, v107
	v_cvt_pk_bf16_f32 v124, v108, v109
	v_cvt_pk_bf16_f32 v125, v110, v111
	v_lshl_add_u64 v[126:127], v[116:117], 1, s[62:63]
	v_add_f32_e32 v104, v105, v104
	v_mul_f32_e32 v105, v111, v111
	global_store_dwordx4 v[126:127], v[122:125], off
	v_fmac_f32_e32 v105, v110, v110
	v_add_f32_e32 v121, v105, v104
	v_or_b32_e32 v116, 0x80, v116
	s_waitcnt vmcnt(3)
	v_mov_b32_e32 v104, v166
	v_mov_b32_e32 v105, v167
	v_mov_b32_e32 v106, v168
	v_mov_b32_e32 v107, v169
	v_mov_b32_e32 v108, v170
	v_mov_b32_e32 v109, v171
	v_mov_b32_e32 v110, v172
	v_mov_b32_e32 v111, v173
	v_pk_fma_f32 v[100:101], v[100:101], v[114:115], v[104:105] op_sel_hi:[1,0,1]
	v_pk_fma_f32 v[98:99], v[98:99], v[114:115], v[110:111] op_sel_hi:[1,0,1]
	v_pk_fma_f32 v[96:97], v[96:97], v[114:115], v[108:109] op_sel_hi:[1,0,1]
	v_lshl_add_u64 v[104:105], v[116:117], 2, s[60:61]
	v_pk_fma_f32 v[102:103], v[102:103], v[114:115], v[106:107] op_sel_hi:[1,0,1]
	global_store_dwordx4 v[104:105], v[96:99], off
	global_store_dwordx4 v[104:105], v[100:103], off offset:16
	v_cvt_pk_bf16_f32 v104, v96, v97
	v_mul_f32_e32 v97, v97, v97
	v_fmac_f32_e32 v97, v96, v96
	v_mul_f32_e32 v96, v99, v99
	v_fmac_f32_e32 v96, v98, v98
	v_add_f32_e32 v96, v97, v96
	v_mul_f32_e32 v97, v101, v101
	v_fmac_f32_e32 v97, v100, v100
	v_add_f32_e32 v96, v97, v96
	v_mul_f32_e32 v97, v103, v103
	v_fmac_f32_e32 v97, v102, v102
	v_add_f32_e32 v96, v97, v96
	v_add_f32_e32 v96, v121, v96
	ds_bpermute_b32 v97, v115, v96
	v_cvt_pk_bf16_f32 v105, v98, v99
	v_cvt_pk_bf16_f32 v106, v100, v101
	v_cvt_pk_bf16_f32 v107, v102, v103
	v_lshl_add_u64 v[108:109], v[116:117], 1, s[62:63]
	s_waitcnt lgkmcnt(0)
	v_add_f32_e32 v96, v96, v97
	ds_bpermute_b32 v97, v120, v96
	global_store_dwordx4 v[108:109], v[104:107], off
	s_and_saveexec_b64 s[14:15], s[48:49]
	s_cbranch_execz .LBB0_1282
	s_waitcnt lgkmcnt(0)
	v_add_f32_e32 v96, v96, v97
	v_mul_f32_e32 v96, 0x4f800000, v96
	v_rndne_f32_e32 v96, v96
	v_mul_f32_e32 v97, 0x2f800000, v96
	v_floor_f32_e32 v97, v97
	v_fmac_f32_e32 v96, 0xcf800000, v97
	v_cvt_u32_f32_e32 v96, v96
	v_cvt_u32_f32_e32 v97, v97
	v_mov_b32_e32 v228, v96
	v_mov_b32_e32 v229, v97
.LBB0_1282:
	s_or_b64 exec, exec, s[14:15]
	v_or_b32_e32 v96, 32, v146
	s_waitcnt lgkmcnt(0)
	v_ashrrev_i32_e32 v97, 31, v96
	s_waitcnt vmcnt(11)
	v_mov_b32_e32 v98, v212
	v_mov_b32_e32 v99, v213
	v_mov_b32_e32 v128, v99
	v_lshlrev_b64 v[100:101], s16, v[128:129]
	v_min_u32_e32 v99, 1, v100
	v_or_b32_e32 v99, v101, v99
	v_lshlrev_b64 v[100:101], 11, v[96:97]
	v_lshl_add_u64 v[100:101], v[100:101], 0, v[130:131]
	v_lshlrev_b64 v[112:113], 2, v[100:101]
	v_lshl_add_u64 v[102:103], s[8:9], 0, v[112:113]
	global_load_dwordx4 v[104:107], v[102:103], off offset:16
	global_load_dwordx4 v[108:111], v[102:103], off
	global_load_dwordx4 v[166:169], v[102:103], off offset:528
	global_load_dwordx4 v[170:173], v[102:103], off offset:512
	v_cvt_f32_u32_e32 v99, v99
	v_cvt_f32_u32_e32 v98, v98
	v_ldexp_f32 v99, v99, s17
	v_fmac_f32_e32 v99, 0x2f800000, v98
	v_fmamk_f32 v98, v99, 0x3b000000, v195
	v_cmp_gt_f32_e32 vcc, s27, v98
	v_mul_f32_e32 v99, 0x4b800000, v98
	s_nop 0
	v_cndmask_b32_e32 v98, v98, v99, vcc
	v_rsq_f32_e32 v98, v98
	s_nop 0
	v_mul_f32_e32 v99, 0x45800000, v98
	v_cndmask_b32_e32 v98, v98, v99, vcc
	s_waitcnt vmcnt(3)
	v_pk_fma_f32 v[92:93], v[92:93], v[98:99], v[104:105] op_sel_hi:[1,0,1]
	s_waitcnt vmcnt(2)
; DI void ss_add(ssacc_t* p, float v) { atomicAdd(p, (ssacc_t)__float2ull_rn(v * 4294967296.f)); }
; DI float ss_get(const ssacc_t* p) { const ssacc_t v = *p; return (float)(unsigned)(v >> 32) + (float)(unsigned)(v & 0xffffffffull) * 2.3283064365386963e-10f; }
; DI float quad_sum(float s) { s += __shfl_xor(s, 16); s += __shfl_xor(s, 32); return s; }
; DI float sq8(const f32x4& a, const f32x4& b) { return (a[0] * a[0] + a[1] * a[1]) + (a[2] * a[2] + a[3] * a[3]) + (b[0] * b[0] + b[1] * b[1]) + (b[2] * b[2] + b[3] * b[3]); }
; DI u32x4 pack8(const f32x4& a, const f32x4& b) { u32x4 w; w.x = cvtpk(a[0], a[1]); w.y = cvtpk(a[2], a[3]); w.z = cvtpk(b[0], b[1]); w.w = cvtpk(b[2], b[3]); return w; }
;     DI void operator()(const Acc& acc, const Unit& u, int wr, int wc, int fr, int fq) const {
;         const ssacc_t* ss_dil = (const ssacc_t*)(ws + WS_SS) + (size_t)(SS_DIL + l) * M_; ssacc_t* ssx1 = (ssacc_t*)(ws + WS_SS) + (size_t)(SS_X1 + l) * M_;
;         float* X = (float*)(ws + WS_X); bf16_t* XB = (bf16_t*)(ws + WS_XB);
; #pragma unroll
;         for (int ai = 0; ai < 2; ++ai)
; #pragma unroll
;             for (int m = 0; m < 4; ++m) {
;                 asm volatile("" ::: "memory");
;                 const int row = u.pm * 256 + ai * 128 + wr * 64 + m * 16 + fr;
;                 const float rs = rsqrtf(ss_get(ss_dil + row) * (1.f / 512.f) + EPS_);
;                 float sq = 0.f;
; #pragma unroll
;                 for (int bj = 0; bj < 2; ++bj) {
;                     const size_t off = (size_t)row * 2048 + u.pn * 256 + bj * 128 + wc * 32 + 8 * fq;
;                     const f32x4 v0 = *(const f32x4*)(xin + off) + acc[ai][bj][m][0] * rs, v1 = *(const f32x4*)(xin + off + 4) + acc[ai][bj][m][1] * rs;
;                     *(f32x4*)(X + off) = v0; *(f32x4*)(X + off + 4) = v1; *(u32x4*)(XB + off) = pack8(v0, v1); sq += sq8(v0, v1);
;                 }
;                 sq = quad_sum(sq); if (fq == 0) ss_add(ssx1 + row, sq);
;             }
;     }
	v_pk_fma_f32 v[90:91], v[90:91], v[98:99], v[110:111] op_sel_hi:[1,0,1]
	v_pk_fma_f32 v[88:89], v[88:89], v[98:99], v[108:109] op_sel_hi:[1,0,1]
	v_lshl_add_u64 v[104:105], s[60:61], 0, v[112:113]
	v_pk_fma_f32 v[94:95], v[94:95], v[98:99], v[106:107] op_sel_hi:[1,0,1]
	global_store_dwordx4 v[104:105], v[88:91], off
	global_store_dwordx4 v[104:105], v[92:95], off offset:16
	v_cvt_pk_bf16_f32 v104, v88, v89
	v_mul_f32_e32 v89, v89, v89
	v_fmac_f32_e32 v89, v88, v88
	v_mul_f32_e32 v88, v91, v91
	v_fmac_f32_e32 v88, v90, v90
	v_add_f32_e32 v88, v89, v88
	v_mul_f32_e32 v89, v93, v93
	v_fmac_f32_e32 v89, v92, v92
	v_cvt_pk_bf16_f32 v105, v90, v91
	v_cvt_pk_bf16_f32 v106, v92, v93
	v_cvt_pk_bf16_f32 v107, v94, v95
	v_lshl_add_u64 v[108:109], v[100:101], 1, s[62:63]
	v_add_f32_e32 v88, v89, v88
	v_mul_f32_e32 v89, v95, v95
	global_store_dwordx4 v[108:109], v[104:107], off
	v_fmac_f32_e32 v89, v94, v94
	v_add_f32_e32 v99, v89, v88
	v_or_b32_e32 v100, 0x80, v100
	s_waitcnt vmcnt(3)
	v_mov_b32_e32 v88, v166
	v_mov_b32_e32 v89, v167
	v_mov_b32_e32 v90, v168
	v_mov_b32_e32 v91, v169
	v_mov_b32_e32 v92, v170
	v_mov_b32_e32 v93, v171
	v_mov_b32_e32 v94, v172
	v_mov_b32_e32 v95, v173
	v_pk_fma_f32 v[84:85], v[84:85], v[98:99], v[88:89] op_sel_hi:[1,0,1]
	v_pk_fma_f32 v[82:83], v[82:83], v[98:99], v[94:95] op_sel_hi:[1,0,1]
	v_pk_fma_f32 v[80:81], v[80:81], v[98:99], v[92:93] op_sel_hi:[1,0,1]
	v_lshl_add_u64 v[88:89], v[100:101], 2, s[60:61]
	v_pk_fma_f32 v[86:87], v[86:87], v[98:99], v[90:91] op_sel_hi:[1,0,1]
	global_store_dwordx4 v[88:89], v[80:83], off
	global_store_dwordx4 v[88:89], v[84:87], off offset:16
	v_cvt_pk_bf16_f32 v88, v80, v81
	v_mul_f32_e32 v81, v81, v81
	v_fmac_f32_e32 v81, v80, v80
	v_mul_f32_e32 v80, v83, v83
	v_fmac_f32_e32 v80, v82, v82
	v_add_f32_e32 v80, v81, v80
	v_mul_f32_e32 v81, v85, v85
	v_fmac_f32_e32 v81, v84, v84
	v_add_f32_e32 v80, v81, v80
	v_mul_f32_e32 v81, v87, v87
	v_fmac_f32_e32 v81, v86, v86
	v_add_f32_e32 v80, v81, v80
	v_add_f32_e32 v80, v99, v80
	ds_bpermute_b32 v81, v115, v80
	v_cvt_pk_bf16_f32 v89, v82, v83
	v_cvt_pk_bf16_f32 v90, v84, v85
	v_cvt_pk_bf16_f32 v91, v86, v87
	v_lshl_add_u64 v[92:93], v[100:101], 1, s[62:63]
	s_waitcnt lgkmcnt(0)
	v_add_f32_e32 v80, v80, v81
	ds_bpermute_b32 v81, v120, v80
	global_store_dwordx4 v[92:93], v[88:91], off
	s_and_saveexec_b64 s[14:15], s[48:49]
	s_cbranch_execz .LBB0_1284
	s_waitcnt lgkmcnt(0)
	v_add_f32_e32 v80, v80, v81
	v_mul_f32_e32 v80, 0x4f800000, v80
	v_rndne_f32_e32 v80, v80
	v_mul_f32_e32 v81, 0x2f800000, v80
	v_floor_f32_e32 v81, v81
	v_fmac_f32_e32 v80, 0xcf800000, v81
	v_cvt_u32_f32_e32 v80, v80
	v_cvt_u32_f32_e32 v81, v81
	v_mov_b32_e32 v230, v80
	v_mov_b32_e32 v231, v81
.LBB0_1284:
	s_or_b64 exec, exec, s[14:15]
	v_or_b32_e32 v80, 48, v146
	s_waitcnt lgkmcnt(0)
	v_ashrrev_i32_e32 v81, 31, v80
	s_waitcnt vmcnt(13)
	v_mov_b32_e32 v82, v214
	v_mov_b32_e32 v83, v215
	v_mov_b32_e32 v128, v83
	v_lshlrev_b64 v[84:85], s16, v[128:129]
	v_min_u32_e32 v83, 1, v84
	v_or_b32_e32 v83, v85, v83
	v_lshlrev_b64 v[84:85], 11, v[80:81]
	v_lshl_add_u64 v[84:85], v[84:85], 0, v[130:131]
	v_lshlrev_b64 v[96:97], 2, v[84:85]
	v_lshl_add_u64 v[86:87], s[8:9], 0, v[96:97]
	global_load_dwordx4 v[88:91], v[86:87], off offset:16
	global_load_dwordx4 v[92:95], v[86:87], off
	global_load_dwordx4 v[166:169], v[86:87], off offset:528
	global_load_dwordx4 v[170:173], v[86:87], off offset:512
	v_cvt_f32_u32_e32 v83, v83
	v_cvt_f32_u32_e32 v82, v82
	v_ldexp_f32 v83, v83, s17
	v_fmac_f32_e32 v83, 0x2f800000, v82
	v_fmamk_f32 v82, v83, 0x3b000000, v195
	v_cmp_gt_f32_e32 vcc, s27, v82
	v_mul_f32_e32 v83, 0x4b800000, v82
	s_nop 0
	v_cndmask_b32_e32 v82, v82, v83, vcc
	v_rsq_f32_e32 v82, v82
	s_nop 0
	v_mul_f32_e32 v83, 0x45800000, v82
	v_cndmask_b32_e32 v82, v82, v83, vcc
	s_waitcnt vmcnt(3)
	v_pk_fma_f32 v[76:77], v[76:77], v[82:83], v[88:89] op_sel_hi:[1,0,1]
	s_waitcnt vmcnt(2)
	v_pk_fma_f32 v[74:75], v[74:75], v[82:83], v[94:95] op_sel_hi:[1,0,1]
	v_pk_fma_f32 v[72:73], v[72:73], v[82:83], v[92:93] op_sel_hi:[1,0,1]
	v_lshl_add_u64 v[88:89], s[60:61], 0, v[96:97]
	v_pk_fma_f32 v[78:79], v[78:79], v[82:83], v[90:91] op_sel_hi:[1,0,1]
	global_store_dwordx4 v[88:89], v[72:75], off
	global_store_dwordx4 v[88:89], v[76:79], off offset:16
	v_cvt_pk_bf16_f32 v88, v72, v73
	v_mul_f32_e32 v73, v73, v73
	v_fmac_f32_e32 v73, v72, v72
	v_mul_f32_e32 v72, v75, v75
	v_fmac_f32_e32 v72, v74, v74
	v_add_f32_e32 v72, v73, v72
	v_mul_f32_e32 v73, v77, v77
	v_fmac_f32_e32 v73, v76, v76
	v_cvt_pk_bf16_f32 v89, v74, v75
	v_cvt_pk_bf16_f32 v90, v76, v77
	v_cvt_pk_bf16_f32 v91, v78, v79
	v_lshl_add_u64 v[92:93], v[84:85], 1, s[62:63]
	v_add_f32_e32 v72, v73, v72
	v_mul_f32_e32 v73, v79, v79
	global_store_dwordx4 v[92:93], v[88:91], off
	v_fmac_f32_e32 v73, v78, v78
	v_add_f32_e32 v83, v73, v72
	v_or_b32_e32 v84, 0x80, v84
	s_waitcnt vmcnt(3)
	v_mov_b32_e32 v72, v166
	v_mov_b32_e32 v73, v167
	v_mov_b32_e32 v74, v168
	v_mov_b32_e32 v75, v169
	v_mov_b32_e32 v76, v170
	v_mov_b32_e32 v77, v171
	v_mov_b32_e32 v78, v172
	v_mov_b32_e32 v79, v173
	v_pk_fma_f32 v[68:69], v[68:69], v[82:83], v[72:73] op_sel_hi:[1,0,1]
	v_pk_fma_f32 v[66:67], v[66:67], v[82:83], v[78:79] op_sel_hi:[1,0,1]
	v_pk_fma_f32 v[64:65], v[64:65], v[82:83], v[76:77] op_sel_hi:[1,0,1]
	v_lshl_add_u64 v[72:73], v[84:85], 2, s[60:61]
	v_pk_fma_f32 v[70:71], v[70:71], v[82:83], v[74:75] op_sel_hi:[1,0,1]
	global_store_dwordx4 v[72:73], v[64:67], off
	global_store_dwordx4 v[72:73], v[68:71], off offset:16
	v_cvt_pk_bf16_f32 v72, v64, v65
	v_mul_f32_e32 v65, v65, v65
	v_fmac_f32_e32 v65, v64, v64
	v_mul_f32_e32 v64, v67, v67
	v_fmac_f32_e32 v64, v66, v66
	v_add_f32_e32 v64, v65, v64
	v_mul_f32_e32 v65, v69, v69
	v_fmac_f32_e32 v65, v68, v68
	v_add_f32_e32 v64, v65, v64
	v_mul_f32_e32 v65, v71, v71
	v_fmac_f32_e32 v65, v70, v70
	v_add_f32_e32 v64, v65, v64
	v_add_f32_e32 v64, v83, v64
	ds_bpermute_b32 v65, v115, v64
	v_cvt_pk_bf16_f32 v73, v66, v67
	v_cvt_pk_bf16_f32 v74, v68, v69
	v_cvt_pk_bf16_f32 v75, v70, v71
	v_lshl_add_u64 v[76:77], v[84:85], 1, s[62:63]
	s_waitcnt lgkmcnt(0)
	v_add_f32_e32 v64, v64, v65
	ds_bpermute_b32 v65, v120, v64
	global_store_dwordx4 v[76:77], v[72:75], off
	s_and_saveexec_b64 s[14:15], s[48:49]
	s_cbranch_execz .LBB0_1286
	s_waitcnt lgkmcnt(0)
	v_add_f32_e32 v64, v64, v65
	v_mul_f32_e32 v64, 0x4f800000, v64
	v_rndne_f32_e32 v64, v64
	v_mul_f32_e32 v65, 0x2f800000, v64
	v_floor_f32_e32 v65, v65
	v_fmac_f32_e32 v64, 0xcf800000, v65
	v_cvt_u32_f32_e32 v64, v64
	v_cvt_u32_f32_e32 v65, v65
	v_mov_b32_e32 v232, v64
	v_mov_b32_e32 v233, v65
; DI void ss_add(ssacc_t* p, float v) { atomicAdd(p, (ssacc_t)__float2ull_rn(v * 4294967296.f)); }
; DI float ss_get(const ssacc_t* p) { const ssacc_t v = *p; return (float)(unsigned)(v >> 32) + (float)(unsigned)(v & 0xffffffffull) * 2.3283064365386963e-10f; }
; DI float quad_sum(float s) { s += __shfl_xor(s, 16); s += __shfl_xor(s, 32); return s; }
; DI float sq8(const f32x4& a, const f32x4& b) { return (a[0] * a[0] + a[1] * a[1]) + (a[2] * a[2] + a[3] * a[3]) + (b[0] * b[0] + b[1] * b[1]) + (b[2] * b[2] + b[3] * b[3]); }
; DI u32x4 pack8(const f32x4& a, const f32x4& b) { u32x4 w; w.x = cvtpk(a[0], a[1]); w.y = cvtpk(a[2], a[3]); w.z = cvtpk(b[0], b[1]); w.w = cvtpk(b[2], b[3]); return w; }
;     DI void operator()(const Acc& acc, const Unit& u, int wr, int wc, int fr, int fq) const {
;         const ssacc_t* ss_dil = (const ssacc_t*)(ws + WS_SS) + (size_t)(SS_DIL + l) * M_; ssacc_t* ssx1 = (ssacc_t*)(ws + WS_SS) + (size_t)(SS_X1 + l) * M_;
;         float* X = (float*)(ws + WS_X); bf16_t* XB = (bf16_t*)(ws + WS_XB);
; #pragma unroll
;         for (int ai = 0; ai < 2; ++ai)
; #pragma unroll
;             for (int m = 0; m < 4; ++m) {
;                 asm volatile("" ::: "memory");
;                 const int row = u.pm * 256 + ai * 128 + wr * 64 + m * 16 + fr;
;                 const float rs = rsqrtf(ss_get(ss_dil + row) * (1.f / 512.f) + EPS_);
;                 float sq = 0.f;
; #pragma unroll
;                 for (int bj = 0; bj < 2; ++bj) {
;                     const size_t off = (size_t)row * 2048 + u.pn * 256 + bj * 128 + wc * 32 + 8 * fq;
;                     const f32x4 v0 = *(const f32x4*)(xin + off) + acc[ai][bj][m][0] * rs, v1 = *(const f32x4*)(xin + off + 4) + acc[ai][bj][m][1] * rs;
;                     *(f32x4*)(X + off) = v0; *(f32x4*)(X + off + 4) = v1; *(u32x4*)(XB + off) = pack8(v0, v1); sq += sq8(v0, v1);
;                 }
;                 sq = quad_sum(sq); if (fq == 0) ss_add(ssx1 + row, sq);
;             }
;     }
.LBB0_1286:
	s_or_b64 exec, exec, s[14:15]
	v_add_u32_e32 v64, 0x80, v146
	s_waitcnt lgkmcnt(0)
	v_ashrrev_i32_e32 v65, 31, v64
	s_waitcnt vmcnt(15)
	v_mov_b32_e32 v66, v216
	v_mov_b32_e32 v67, v217
	v_mov_b32_e32 v128, v67
	v_lshlrev_b64 v[68:69], s16, v[128:129]
	v_min_u32_e32 v67, 1, v68
	v_or_b32_e32 v67, v69, v67
	v_lshlrev_b64 v[68:69], 11, v[64:65]
	v_lshl_add_u64 v[68:69], v[68:69], 0, v[130:131]
	v_lshlrev_b64 v[80:81], 2, v[68:69]
	v_lshl_add_u64 v[70:71], s[8:9], 0, v[80:81]
	global_load_dwordx4 v[72:75], v[70:71], off offset:16
	global_load_dwordx4 v[76:79], v[70:71], off
	global_load_dwordx4 v[166:169], v[70:71], off offset:528
	global_load_dwordx4 v[170:173], v[70:71], off offset:512
	v_cvt_f32_u32_e32 v67, v67
	v_cvt_f32_u32_e32 v66, v66
	v_ldexp_f32 v67, v67, s17
	v_fmac_f32_e32 v67, 0x2f800000, v66
	v_fmamk_f32 v66, v67, 0x3b000000, v195
	v_cmp_gt_f32_e32 vcc, s27, v66
	v_mul_f32_e32 v67, 0x4b800000, v66
	s_nop 0
	v_cndmask_b32_e32 v66, v66, v67, vcc
	v_rsq_f32_e32 v66, v66
	s_nop 0
	v_mul_f32_e32 v67, 0x45800000, v66
	v_cndmask_b32_e32 v66, v66, v67, vcc
	s_waitcnt vmcnt(3)
	v_pk_fma_f32 v[60:61], v[60:61], v[66:67], v[72:73] op_sel_hi:[1,0,1]
	s_waitcnt vmcnt(2)
	v_pk_fma_f32 v[58:59], v[58:59], v[66:67], v[78:79] op_sel_hi:[1,0,1]
	v_pk_fma_f32 v[56:57], v[56:57], v[66:67], v[76:77] op_sel_hi:[1,0,1]
	v_lshl_add_u64 v[72:73], s[60:61], 0, v[80:81]
	v_pk_fma_f32 v[62:63], v[62:63], v[66:67], v[74:75] op_sel_hi:[1,0,1]
	global_store_dwordx4 v[72:73], v[56:59], off
	global_store_dwordx4 v[72:73], v[60:63], off offset:16
	v_cvt_pk_bf16_f32 v72, v56, v57
	v_mul_f32_e32 v57, v57, v57
	v_fmac_f32_e32 v57, v56, v56
	v_mul_f32_e32 v56, v59, v59
	v_fmac_f32_e32 v56, v58, v58
	v_add_f32_e32 v56, v57, v56
	v_mul_f32_e32 v57, v61, v61
	v_fmac_f32_e32 v57, v60, v60
	v_cvt_pk_bf16_f32 v73, v58, v59
	v_cvt_pk_bf16_f32 v74, v60, v61
	v_cvt_pk_bf16_f32 v75, v62, v63
	v_lshl_add_u64 v[76:77], v[68:69], 1, s[62:63]
	v_add_f32_e32 v56, v57, v56
	v_mul_f32_e32 v57, v63, v63
	global_store_dwordx4 v[76:77], v[72:75], off
	v_fmac_f32_e32 v57, v62, v62
	v_add_f32_e32 v67, v57, v56
	v_or_b32_e32 v68, 0x80, v68
	s_waitcnt vmcnt(3)
	v_mov_b32_e32 v56, v166
	v_mov_b32_e32 v57, v167
	v_mov_b32_e32 v58, v168
	v_mov_b32_e32 v59, v169
	v_mov_b32_e32 v60, v170
	v_mov_b32_e32 v61, v171
	v_mov_b32_e32 v62, v172
	v_mov_b32_e32 v63, v173
	v_pk_fma_f32 v[52:53], v[52:53], v[66:67], v[56:57] op_sel_hi:[1,0,1]
	v_pk_fma_f32 v[50:51], v[50:51], v[66:67], v[62:63] op_sel_hi:[1,0,1]
	v_pk_fma_f32 v[48:49], v[48:49], v[66:67], v[60:61] op_sel_hi:[1,0,1]
	v_lshl_add_u64 v[56:57], v[68:69], 2, s[60:61]
	v_pk_fma_f32 v[54:55], v[54:55], v[66:67], v[58:59] op_sel_hi:[1,0,1]
	global_store_dwordx4 v[56:57], v[48:51], off
	global_store_dwordx4 v[56:57], v[52:55], off offset:16
	v_cvt_pk_bf16_f32 v56, v48, v49
	v_mul_f32_e32 v49, v49, v49
	v_fmac_f32_e32 v49, v48, v48
	v_mul_f32_e32 v48, v51, v51
	v_fmac_f32_e32 v48, v50, v50
	v_add_f32_e32 v48, v49, v48
	v_mul_f32_e32 v49, v53, v53
	v_fmac_f32_e32 v49, v52, v52
	v_add_f32_e32 v48, v49, v48
	v_mul_f32_e32 v49, v55, v55
	v_fmac_f32_e32 v49, v54, v54
	v_add_f32_e32 v48, v49, v48
	v_add_f32_e32 v48, v67, v48
	ds_bpermute_b32 v49, v115, v48
	v_cvt_pk_bf16_f32 v57, v50, v51
	v_cvt_pk_bf16_f32 v58, v52, v53
	v_cvt_pk_bf16_f32 v59, v54, v55
	v_lshl_add_u64 v[60:61], v[68:69], 1, s[62:63]
	s_waitcnt lgkmcnt(0)
	v_add_f32_e32 v48, v48, v49
	ds_bpermute_b32 v49, v120, v48
	global_store_dwordx4 v[60:61], v[56:59], off
	s_and_saveexec_b64 s[14:15], s[48:49]
	s_cbranch_execz .LBB0_1288
	s_waitcnt lgkmcnt(0)
	v_add_f32_e32 v48, v48, v49
	v_mul_f32_e32 v48, 0x4f800000, v48
	v_rndne_f32_e32 v48, v48
	v_mul_f32_e32 v49, 0x2f800000, v48
	v_floor_f32_e32 v49, v49
	v_fmac_f32_e32 v48, 0xcf800000, v49
	v_cvt_u32_f32_e32 v48, v48
	v_cvt_u32_f32_e32 v49, v49
	v_mov_b32_e32 v234, v48
	v_mov_b32_e32 v235, v49
.LBB0_1288:
	s_or_b64 exec, exec, s[14:15]
	v_add_u32_e32 v48, 0x90, v146
	s_waitcnt lgkmcnt(0)
	v_ashrrev_i32_e32 v49, 31, v48
	s_waitcnt vmcnt(17)
	v_mov_b32_e32 v50, v218
	v_mov_b32_e32 v51, v219
	v_mov_b32_e32 v128, v51
	v_lshlrev_b64 v[52:53], s16, v[128:129]
	v_min_u32_e32 v51, 1, v52
	v_or_b32_e32 v51, v53, v51
	v_lshlrev_b64 v[52:53], 11, v[48:49]
	v_lshl_add_u64 v[52:53], v[52:53], 0, v[130:131]
	v_lshlrev_b64 v[64:65], 2, v[52:53]
	v_lshl_add_u64 v[54:55], s[8:9], 0, v[64:65]
	global_load_dwordx4 v[56:59], v[54:55], off offset:16
	global_load_dwordx4 v[60:63], v[54:55], off
	global_load_dwordx4 v[166:169], v[54:55], off offset:528
	global_load_dwordx4 v[170:173], v[54:55], off offset:512
	v_cvt_f32_u32_e32 v51, v51
	v_cvt_f32_u32_e32 v50, v50
	v_ldexp_f32 v51, v51, s17
	v_fmac_f32_e32 v51, 0x2f800000, v50
	v_fmamk_f32 v50, v51, 0x3b000000, v195
	v_cmp_gt_f32_e32 vcc, s27, v50
	v_mul_f32_e32 v51, 0x4b800000, v50
	s_nop 0
	v_cndmask_b32_e32 v50, v50, v51, vcc
	v_rsq_f32_e32 v50, v50
	s_nop 0
	v_mul_f32_e32 v51, 0x45800000, v50
	v_cndmask_b32_e32 v50, v50, v51, vcc
	s_waitcnt vmcnt(3)
	v_pk_fma_f32 v[44:45], v[44:45], v[50:51], v[56:57] op_sel_hi:[1,0,1]
	s_waitcnt vmcnt(2)
	v_pk_fma_f32 v[42:43], v[42:43], v[50:51], v[62:63] op_sel_hi:[1,0,1]
	v_pk_fma_f32 v[40:41], v[40:41], v[50:51], v[60:61] op_sel_hi:[1,0,1]
	v_lshl_add_u64 v[56:57], s[60:61], 0, v[64:65]
	v_pk_fma_f32 v[46:47], v[46:47], v[50:51], v[58:59] op_sel_hi:[1,0,1]
	global_store_dwordx4 v[56:57], v[40:43], off
	global_store_dwordx4 v[56:57], v[44:47], off offset:16
	v_cvt_pk_bf16_f32 v56, v40, v41
	v_mul_f32_e32 v41, v41, v41
	v_fmac_f32_e32 v41, v40, v40
	v_mul_f32_e32 v40, v43, v43
	v_fmac_f32_e32 v40, v42, v42
	v_add_f32_e32 v40, v41, v40
	v_mul_f32_e32 v41, v45, v45
	v_fmac_f32_e32 v41, v44, v44
	v_cvt_pk_bf16_f32 v57, v42, v43
	v_cvt_pk_bf16_f32 v58, v44, v45
	v_cvt_pk_bf16_f32 v59, v46, v47
	v_lshl_add_u64 v[60:61], v[52:53], 1, s[62:63]
	v_add_f32_e32 v40, v41, v40
	v_mul_f32_e32 v41, v47, v47
	global_store_dwordx4 v[60:61], v[56:59], off
	v_fmac_f32_e32 v41, v46, v46
	v_add_f32_e32 v51, v41, v40
	v_or_b32_e32 v52, 0x80, v52
	s_waitcnt vmcnt(3)
; DI void ss_add(ssacc_t* p, float v) { atomicAdd(p, (ssacc_t)__float2ull_rn(v * 4294967296.f)); }
; DI float ss_get(const ssacc_t* p) { const ssacc_t v = *p; return (float)(unsigned)(v >> 32) + (float)(unsigned)(v & 0xffffffffull) * 2.3283064365386963e-10f; }
; DI float quad_sum(float s) { s += __shfl_xor(s, 16); s += __shfl_xor(s, 32); return s; }
; DI float sq8(const f32x4& a, const f32x4& b) { return (a[0] * a[0] + a[1] * a[1]) + (a[2] * a[2] + a[3] * a[3]) + (b[0] * b[0] + b[1] * b[1]) + (b[2] * b[2] + b[3] * b[3]); }
; DI u32x4 pack8(const f32x4& a, const f32x4& b) { u32x4 w; w.x = cvtpk(a[0], a[1]); w.y = cvtpk(a[2], a[3]); w.z = cvtpk(b[0], b[1]); w.w = cvtpk(b[2], b[3]); return w; }
;     DI void operator()(const Acc& acc, const Unit& u, int wr, int wc, int fr, int fq) const {
;         const ssacc_t* ss_dil = (const ssacc_t*)(ws + WS_SS) + (size_t)(SS_DIL + l) * M_; ssacc_t* ssx1 = (ssacc_t*)(ws + WS_SS) + (size_t)(SS_X1 + l) * M_;
;         float* X = (float*)(ws + WS_X); bf16_t* XB = (bf16_t*)(ws + WS_XB);
; #pragma unroll
;         for (int ai = 0; ai < 2; ++ai)
; #pragma unroll
;             for (int m = 0; m < 4; ++m) {
;                 asm volatile("" ::: "memory");
;                 const int row = u.pm * 256 + ai * 128 + wr * 64 + m * 16 + fr;
;                 const float rs = rsqrtf(ss_get(ss_dil + row) * (1.f / 512.f) + EPS_);
;                 float sq = 0.f;
; #pragma unroll
;                 for (int bj = 0; bj < 2; ++bj) {
;                     const size_t off = (size_t)row * 2048 + u.pn * 256 + bj * 128 + wc * 32 + 8 * fq;
;                     const f32x4 v0 = *(const f32x4*)(xin + off) + acc[ai][bj][m][0] * rs, v1 = *(const f32x4*)(xin + off + 4) + acc[ai][bj][m][1] * rs;
;                     *(f32x4*)(X + off) = v0; *(f32x4*)(X + off + 4) = v1; *(u32x4*)(XB + off) = pack8(v0, v1); sq += sq8(v0, v1);
;                 }
;                 sq = quad_sum(sq); if (fq == 0) ss_add(ssx1 + row, sq);
;             }
;     }
	v_mov_b32_e32 v40, v166
	v_mov_b32_e32 v41, v167
	v_mov_b32_e32 v42, v168
	v_mov_b32_e32 v43, v169
	v_mov_b32_e32 v44, v170
	v_mov_b32_e32 v45, v171
	v_mov_b32_e32 v46, v172
	v_mov_b32_e32 v47, v173
	v_pk_fma_f32 v[36:37], v[36:37], v[50:51], v[40:41] op_sel_hi:[1,0,1]
	v_pk_fma_f32 v[34:35], v[34:35], v[50:51], v[46:47] op_sel_hi:[1,0,1]
	v_pk_fma_f32 v[32:33], v[32:33], v[50:51], v[44:45] op_sel_hi:[1,0,1]
	v_lshl_add_u64 v[40:41], v[52:53], 2, s[60:61]
	v_pk_fma_f32 v[38:39], v[38:39], v[50:51], v[42:43] op_sel_hi:[1,0,1]
	global_store_dwordx4 v[40:41], v[32:35], off
	global_store_dwordx4 v[40:41], v[36:39], off offset:16
	v_cvt_pk_bf16_f32 v40, v32, v33
	v_mul_f32_e32 v33, v33, v33
	v_fmac_f32_e32 v33, v32, v32
	v_mul_f32_e32 v32, v35, v35
	v_fmac_f32_e32 v32, v34, v34
	v_add_f32_e32 v32, v33, v32
	v_mul_f32_e32 v33, v37, v37
	v_fmac_f32_e32 v33, v36, v36
	v_add_f32_e32 v32, v33, v32
	v_mul_f32_e32 v33, v39, v39
	v_fmac_f32_e32 v33, v38, v38
	v_add_f32_e32 v32, v33, v32
	v_add_f32_e32 v32, v51, v32
	ds_bpermute_b32 v33, v115, v32
	v_cvt_pk_bf16_f32 v41, v34, v35
	v_cvt_pk_bf16_f32 v42, v36, v37
	v_cvt_pk_bf16_f32 v43, v38, v39
	v_lshl_add_u64 v[44:45], v[52:53], 1, s[62:63]
	s_waitcnt lgkmcnt(0)
	v_add_f32_e32 v32, v32, v33
	ds_bpermute_b32 v33, v120, v32
	global_store_dwordx4 v[44:45], v[40:43], off
	s_and_saveexec_b64 s[14:15], s[48:49]
	s_cbranch_execz .LBB0_1290
	s_waitcnt lgkmcnt(0)
	v_add_f32_e32 v32, v32, v33
	v_mul_f32_e32 v32, 0x4f800000, v32
	v_rndne_f32_e32 v32, v32
	v_mul_f32_e32 v33, 0x2f800000, v32
	v_floor_f32_e32 v33, v33
	v_fmac_f32_e32 v32, 0xcf800000, v33
	v_cvt_u32_f32_e32 v32, v32
	v_cvt_u32_f32_e32 v33, v33
	v_mov_b32_e32 v236, v32
	v_mov_b32_e32 v237, v33
.LBB0_1290:
	s_or_b64 exec, exec, s[14:15]
	v_add_u32_e32 v32, 0xa0, v146
	s_waitcnt lgkmcnt(0)
	v_ashrrev_i32_e32 v33, 31, v32
	s_waitcnt vmcnt(19)
	v_mov_b32_e32 v34, v220
	v_mov_b32_e32 v35, v221
	v_mov_b32_e32 v128, v35
	v_lshlrev_b64 v[36:37], s16, v[128:129]
	v_min_u32_e32 v35, 1, v36
	v_or_b32_e32 v35, v37, v35
	v_lshlrev_b64 v[36:37], 11, v[32:33]
	v_lshl_add_u64 v[36:37], v[36:37], 0, v[130:131]
	v_lshlrev_b64 v[48:49], 2, v[36:37]
	v_lshl_add_u64 v[38:39], s[8:9], 0, v[48:49]
	global_load_dwordx4 v[40:43], v[38:39], off offset:16
	global_load_dwordx4 v[44:47], v[38:39], off
	global_load_dwordx4 v[166:169], v[38:39], off offset:528
	global_load_dwordx4 v[170:173], v[38:39], off offset:512
	v_cvt_f32_u32_e32 v35, v35
	v_cvt_f32_u32_e32 v34, v34
	v_ldexp_f32 v35, v35, s17
	v_fmac_f32_e32 v35, 0x2f800000, v34
	v_fmamk_f32 v34, v35, 0x3b000000, v195
	v_cmp_gt_f32_e32 vcc, s27, v34
	v_mul_f32_e32 v35, 0x4b800000, v34
	s_nop 0
	v_cndmask_b32_e32 v34, v34, v35, vcc
	v_rsq_f32_e32 v34, v34
	s_nop 0
	v_mul_f32_e32 v35, 0x45800000, v34
	v_cndmask_b32_e32 v34, v34, v35, vcc
	s_waitcnt vmcnt(3)
	v_pk_fma_f32 v[28:29], v[28:29], v[34:35], v[40:41] op_sel_hi:[1,0,1]
	s_waitcnt vmcnt(2)
	v_pk_fma_f32 v[26:27], v[26:27], v[34:35], v[46:47] op_sel_hi:[1,0,1]
	v_pk_fma_f32 v[24:25], v[24:25], v[34:35], v[44:45] op_sel_hi:[1,0,1]
	v_lshl_add_u64 v[40:41], s[60:61], 0, v[48:49]
	v_pk_fma_f32 v[30:31], v[30:31], v[34:35], v[42:43] op_sel_hi:[1,0,1]
	global_store_dwordx4 v[40:41], v[24:27], off
	global_store_dwordx4 v[40:41], v[28:31], off offset:16
	v_cvt_pk_bf16_f32 v40, v24, v25
	v_mul_f32_e32 v25, v25, v25
	v_fmac_f32_e32 v25, v24, v24
	v_mul_f32_e32 v24, v27, v27
	v_fmac_f32_e32 v24, v26, v26
	v_add_f32_e32 v24, v25, v24
	v_mul_f32_e32 v25, v29, v29
	v_fmac_f32_e32 v25, v28, v28
	v_cvt_pk_bf16_f32 v41, v26, v27
	v_cvt_pk_bf16_f32 v42, v28, v29
	v_cvt_pk_bf16_f32 v43, v30, v31
	v_lshl_add_u64 v[44:45], v[36:37], 1, s[62:63]
	v_add_f32_e32 v24, v25, v24
	v_mul_f32_e32 v25, v31, v31
	global_store_dwordx4 v[44:45], v[40:43], off
	v_fmac_f32_e32 v25, v30, v30
	v_add_f32_e32 v35, v25, v24
	v_or_b32_e32 v36, 0x80, v36
	s_waitcnt vmcnt(3)
	v_mov_b32_e32 v24, v166
	v_mov_b32_e32 v25, v167
	v_mov_b32_e32 v26, v168
	v_mov_b32_e32 v27, v169
	v_mov_b32_e32 v28, v170
	v_mov_b32_e32 v29, v171
	v_mov_b32_e32 v30, v172
	v_mov_b32_e32 v31, v173
	v_pk_fma_f32 v[20:21], v[20:21], v[34:35], v[24:25] op_sel_hi:[1,0,1]
	v_pk_fma_f32 v[18:19], v[18:19], v[34:35], v[30:31] op_sel_hi:[1,0,1]
	v_pk_fma_f32 v[16:17], v[16:17], v[34:35], v[28:29] op_sel_hi:[1,0,1]
	v_lshl_add_u64 v[24:25], v[36:37], 2, s[60:61]
	v_pk_fma_f32 v[22:23], v[22:23], v[34:35], v[26:27] op_sel_hi:[1,0,1]
	global_store_dwordx4 v[24:25], v[16:19], off
	global_store_dwordx4 v[24:25], v[20:23], off offset:16
	v_cvt_pk_bf16_f32 v24, v16, v17
	v_mul_f32_e32 v17, v17, v17
	v_fmac_f32_e32 v17, v16, v16
	v_mul_f32_e32 v16, v19, v19
	v_fmac_f32_e32 v16, v18, v18
	v_add_f32_e32 v16, v17, v16
	v_mul_f32_e32 v17, v21, v21
	v_fmac_f32_e32 v17, v20, v20
	v_add_f32_e32 v16, v17, v16
	v_mul_f32_e32 v17, v23, v23
	v_fmac_f32_e32 v17, v22, v22
	v_add_f32_e32 v16, v17, v16
	v_add_f32_e32 v16, v35, v16
	ds_bpermute_b32 v17, v115, v16
	v_cvt_pk_bf16_f32 v25, v18, v19
	v_cvt_pk_bf16_f32 v26, v20, v21
	v_cvt_pk_bf16_f32 v27, v22, v23
	v_lshl_add_u64 v[28:29], v[36:37], 1, s[62:63]
	s_waitcnt lgkmcnt(0)
	v_add_f32_e32 v16, v16, v17
	ds_bpermute_b32 v17, v120, v16
	global_store_dwordx4 v[28:29], v[24:27], off
	s_and_saveexec_b64 s[14:15], s[48:49]
	s_cbranch_execz .LBB0_1292
	s_waitcnt lgkmcnt(0)
	v_add_f32_e32 v16, v16, v17
	v_mul_f32_e32 v16, 0x4f800000, v16
	v_rndne_f32_e32 v16, v16
	v_mul_f32_e32 v17, 0x2f800000, v16
	v_floor_f32_e32 v17, v17
	v_fmac_f32_e32 v16, 0xcf800000, v17
	v_cvt_u32_f32_e32 v16, v16
	v_cvt_u32_f32_e32 v17, v17
	v_mov_b32_e32 v238, v16
	v_mov_b32_e32 v239, v17
; DI void ss_add(ssacc_t* p, float v) { atomicAdd(p, (ssacc_t)__float2ull_rn(v * 4294967296.f)); }
; DI float ss_get(const ssacc_t* p) { const ssacc_t v = *p; return (float)(unsigned)(v >> 32) + (float)(unsigned)(v & 0xffffffffull) * 2.3283064365386963e-10f; }
; DI float quad_sum(float s) { s += __shfl_xor(s, 16); s += __shfl_xor(s, 32); return s; }
; DI float sq8(const f32x4& a, const f32x4& b) { return (a[0] * a[0] + a[1] * a[1]) + (a[2] * a[2] + a[3] * a[3]) + (b[0] * b[0] + b[1] * b[1]) + (b[2] * b[2] + b[3] * b[3]); }
; DI u32x4 pack8(const f32x4& a, const f32x4& b) { u32x4 w; w.x = cvtpk(a[0], a[1]); w.y = cvtpk(a[2], a[3]); w.z = cvtpk(b[0], b[1]); w.w = cvtpk(b[2], b[3]); return w; }
;     DI void operator()(const Acc& acc, const Unit& u, int wr, int wc, int fr, int fq) const {
;         const ssacc_t* ss_dil = (const ssacc_t*)(ws + WS_SS) + (size_t)(SS_DIL + l) * M_; ssacc_t* ssx1 = (ssacc_t*)(ws + WS_SS) + (size_t)(SS_X1 + l) * M_;
;         float* X = (float*)(ws + WS_X); bf16_t* XB = (bf16_t*)(ws + WS_XB);
; #pragma unroll
;         for (int ai = 0; ai < 2; ++ai)
; #pragma unroll
;             for (int m = 0; m < 4; ++m) {
;                 asm volatile("" ::: "memory");
;                 const int row = u.pm * 256 + ai * 128 + wr * 64 + m * 16 + fr;
;                 const float rs = rsqrtf(ss_get(ss_dil + row) * (1.f / 512.f) + EPS_);
;                 float sq = 0.f;
; #pragma unroll
;                 for (int bj = 0; bj < 2; ++bj) {
;                     const size_t off = (size_t)row * 2048 + u.pn * 256 + bj * 128 + wc * 32 + 8 * fq;
;                     const f32x4 v0 = *(const f32x4*)(xin + off) + acc[ai][bj][m][0] * rs, v1 = *(const f32x4*)(xin + off + 4) + acc[ai][bj][m][1] * rs;
;                     *(f32x4*)(X + off) = v0; *(f32x4*)(X + off + 4) = v1; *(u32x4*)(XB + off) = pack8(v0, v1); sq += sq8(v0, v1);
;                 }
;                 sq = quad_sum(sq); if (fq == 0) ss_add(ssx1 + row, sq);
;             }
;     }
.LBB0_1292:
	s_or_b64 exec, exec, s[14:15]
	v_add_u32_e32 v16, 0xb0, v146
	s_waitcnt lgkmcnt(0)
	v_ashrrev_i32_e32 v17, 31, v16
	s_waitcnt vmcnt(21)
	v_mov_b32_e32 v18, v222
	v_mov_b32_e32 v19, v223
	v_mov_b32_e32 v128, v19
	v_lshlrev_b64 v[20:21], s16, v[128:129]
	v_min_u32_e32 v19, 1, v20
	v_or_b32_e32 v19, v21, v19
	v_lshlrev_b64 v[20:21], 11, v[16:17]
	v_lshl_add_u64 v[20:21], v[20:21], 0, v[130:131]
	v_lshlrev_b64 v[32:33], 2, v[20:21]
	v_lshl_add_u64 v[22:23], s[8:9], 0, v[32:33]
	global_load_dwordx4 v[24:27], v[22:23], off offset:16
	global_load_dwordx4 v[28:31], v[22:23], off
	global_load_dwordx4 v[166:169], v[22:23], off offset:528
	global_load_dwordx4 v[170:173], v[22:23], off offset:512
	v_cvt_f32_u32_e32 v19, v19
	v_cvt_f32_u32_e32 v18, v18
	v_ldexp_f32 v19, v19, s17
	v_fmac_f32_e32 v19, 0x2f800000, v18
	v_fmamk_f32 v18, v19, 0x3b000000, v195
	v_cmp_gt_f32_e32 vcc, s27, v18
	v_mul_f32_e32 v19, 0x4b800000, v18
	s_nop 0
	v_cndmask_b32_e32 v18, v18, v19, vcc
	v_rsq_f32_e32 v18, v18
	s_nop 0
	v_mul_f32_e32 v19, 0x45800000, v18
	v_cndmask_b32_e32 v18, v18, v19, vcc
	s_waitcnt vmcnt(3)
	v_pk_fma_f32 v[12:13], v[12:13], v[18:19], v[24:25] op_sel_hi:[1,0,1]
	s_waitcnt vmcnt(2)
	v_pk_fma_f32 v[10:11], v[10:11], v[18:19], v[30:31] op_sel_hi:[1,0,1]
	v_pk_fma_f32 v[8:9], v[8:9], v[18:19], v[28:29] op_sel_hi:[1,0,1]
	v_lshl_add_u64 v[24:25], s[60:61], 0, v[32:33]
	v_pk_fma_f32 v[14:15], v[14:15], v[18:19], v[26:27] op_sel_hi:[1,0,1]
	global_store_dwordx4 v[24:25], v[8:11], off
	global_store_dwordx4 v[24:25], v[12:15], off offset:16
	v_cvt_pk_bf16_f32 v24, v8, v9
	v_mul_f32_e32 v9, v9, v9
	v_fmac_f32_e32 v9, v8, v8
	v_mul_f32_e32 v8, v11, v11
	v_fmac_f32_e32 v8, v10, v10
	v_add_f32_e32 v8, v9, v8
	v_mul_f32_e32 v9, v13, v13
	v_fmac_f32_e32 v9, v12, v12
	v_cvt_pk_bf16_f32 v25, v10, v11
	v_cvt_pk_bf16_f32 v26, v12, v13
	v_cvt_pk_bf16_f32 v27, v14, v15
	v_lshl_add_u64 v[28:29], v[20:21], 1, s[62:63]
	v_add_f32_e32 v8, v9, v8
	v_mul_f32_e32 v9, v15, v15
	global_store_dwordx4 v[28:29], v[24:27], off
	v_fmac_f32_e32 v9, v14, v14
	v_add_f32_e32 v19, v9, v8
	v_or_b32_e32 v20, 0x80, v20
	s_waitcnt vmcnt(3)
	v_mov_b32_e32 v8, v166
	v_mov_b32_e32 v9, v167
	v_mov_b32_e32 v10, v168
	v_mov_b32_e32 v11, v169
	v_mov_b32_e32 v12, v170
	v_mov_b32_e32 v13, v171
	v_mov_b32_e32 v14, v172
	v_mov_b32_e32 v15, v173
	v_pk_fma_f32 v[4:5], v[4:5], v[18:19], v[8:9] op_sel_hi:[1,0,1]
	v_pk_fma_f32 v[2:3], v[2:3], v[18:19], v[14:15] op_sel_hi:[1,0,1]
	v_pk_fma_f32 v[0:1], v[0:1], v[18:19], v[12:13] op_sel_hi:[1,0,1]
	v_lshl_add_u64 v[8:9], v[20:21], 2, s[60:61]
	v_pk_fma_f32 v[6:7], v[6:7], v[18:19], v[10:11] op_sel_hi:[1,0,1]
	global_store_dwordx4 v[8:9], v[0:3], off
	global_store_dwordx4 v[8:9], v[4:7], off offset:16
	v_cvt_pk_bf16_f32 v8, v0, v1
	v_mul_f32_e32 v1, v1, v1
	v_fmac_f32_e32 v1, v0, v0
	v_mul_f32_e32 v0, v3, v3
	v_fmac_f32_e32 v0, v2, v2
	v_add_f32_e32 v0, v1, v0
	v_mul_f32_e32 v1, v5, v5
	v_fmac_f32_e32 v1, v4, v4
	v_add_f32_e32 v0, v1, v0
	v_mul_f32_e32 v1, v7, v7
	v_fmac_f32_e32 v1, v6, v6
	v_add_f32_e32 v0, v1, v0
	v_add_f32_e32 v0, v19, v0
	ds_bpermute_b32 v1, v115, v0
	v_cvt_pk_bf16_f32 v9, v2, v3
	v_cvt_pk_bf16_f32 v10, v4, v5
	v_cvt_pk_bf16_f32 v11, v6, v7
	v_lshl_add_u64 v[12:13], v[20:21], 1, s[62:63]
	s_waitcnt lgkmcnt(0)
	v_add_f32_e32 v0, v0, v1
	ds_bpermute_b32 v1, v120, v0
	global_store_dwordx4 v[12:13], v[8:11], off
	s_and_saveexec_b64 s[14:15], s[48:49]
	s_cbranch_execz .LBB0_1294
	s_waitcnt lgkmcnt(0)
	v_add_f32_e32 v0, v0, v1
	v_mul_f32_e32 v0, 0x4f800000, v0
	v_rndne_f32_e32 v0, v0
	v_mul_f32_e32 v1, 0x2f800000, v0
	v_floor_f32_e32 v1, v1
	v_fmac_f32_e32 v0, 0xcf800000, v1
	v_cvt_u32_f32_e32 v0, v0
	v_cvt_u32_f32_e32 v1, v1
	v_lshl_add_u64 v[2:3], v[16:17], 3, s[58:59]
	global_atomic_add_x2 v[224:225], v[226:227], off
	global_atomic_add_x2 v[224:225], v[228:229], off offset:128
	global_atomic_add_x2 v[224:225], v[230:231], off offset:256
	global_atomic_add_x2 v[224:225], v[232:233], off offset:384
	global_atomic_add_x2 v[224:225], v[234:235], off offset:1024
	global_atomic_add_x2 v[224:225], v[236:237], off offset:1152
	global_atomic_add_x2 v[224:225], v[238:239], off offset:1280
	global_atomic_add_x2 v[2:3], v[0:1], off
